# v110 with the next-tile row loads issued before the weight loads in the LRU end-of-tile block
# baseline (speedup 1.0000x reference)
; DI unsigned cvtpk(float lo, float hi) { unsigned r; asm volatile("v_cvt_pk_bf16_f32 %0, %1, %2" : "=v"(r) : "v"(lo), "v"(hi)); return r; }
; DI void lru_tile(const Params& p, unsigned char* shm, int c, int nb, const LruPar par) {
;     ...
;         float carry[8], pref[8]; float cin = 0.f, pa = 1.f;
; #pragma unroll
;         for (int gi = 0; gi < 32; ++gi) {
;             const int G = d == 0 ? gi : 31 - gi; const int rt = G >> 2, qq = G & 3;
;             const f32x2 ah = AG[G * 16 + col];
;             if (qq == q) { carry[rt] = cin; pref[rt] = pa; }
;             cin = fmaf(ah[0], cin, ah[1]); pa *= ah[0];
;         }
;         if (q == 0) AGG[((size_t)d * 128 + c) * 2048 + chg] = (f32x2){pa, cin};
; #pragma unroll
;         for (int rt = 0; rt < 8; ++rt) {
;             const f32x2 cr2 = {carry[rt], carry[rt]}, pf2 = {pref[rt] * 255.f, pref[rt] * 255.f}, half2 = {0.5f, 0.5f};
; #pragma unroll
;             for (int jp = 0; jp < 2; ++jp) {
;                 const f32x2 pc2 = {pc[rt][2 * jp], pc[rt][2 * jp + 1]}, hl2 = {hl[rt][2 * jp], hl[rt][2 * jp + 1]};
;                 const f32x2 hf = pc2 * cr2 + hl2, pq = pc2 * pf2 + half2;
;                 const unsigned q0 = (unsigned)pq[0], q1 = (unsigned)pq[1];
;                 if (d == 0) { hsum[rt][2 * jp] = hf[0]; hsum[rt][2 * jp + 1] = hf[1]; ppk[rt][jp] = q0 | (q1 << 16); }
;                 else {
;                     const int lo = (rt * 16 + 4 * q + 2 * jp) * LDU + chl;
;                     const unsigned w = cvtpk(hsum[rt][2 * jp] + hf[0], hsum[rt][2 * jp + 1] + hf[1]);
;                     OS[lo] = (unsigned short)(w & 0xffffu); OS[lo + LDU] = (unsigned short)(w >> 16);
;                     const unsigned pw = ppk[rt][jp] | (q0 << 8) | (q1 << 24);
;                     PS[lo] = (unsigned short)(pw & 0xffffu); PS[lo + LDU] = (unsigned short)(pw >> 16);
;                 }
.LBB0_211:
	s_or_b64 exec, exec, s[60:61]
	v_cndmask_b32_e64 v56, v90, 0, s[10:11]
	v_cndmask_b32_e64 v56, v56, v119, s[4:5]
	v_cndmask_b32_e64 v56, v56, v127, s[6:7]
	v_cndmask_b32_e64 v178, v56, v129, s[8:9]
	v_cndmask_b32_e64 v56, v88, v137, s[10:11]
	v_cndmask_b32_e64 v56, v56, v139, s[4:5]
	v_cndmask_b32_e64 v56, v56, v147, s[6:7]
	v_cndmask_b32_e64 v238, v56, v149, s[8:9]
	v_cndmask_b32_e64 v56, v84, v157, s[10:11]
	v_cndmask_b32_e64 v56, v56, v159, s[4:5]
	v_cndmask_b32_e64 v56, v56, v183, s[6:7]
	v_cndmask_b32_e64 v184, v56, v184, s[8:9]
	v_cndmask_b32_e64 v56, v80, v185, s[10:11]
	v_cndmask_b32_e64 v56, v56, v186, s[4:5]
	v_cndmask_b32_e64 v56, v56, v187, s[6:7]
	v_cndmask_b32_e64 v186, v56, v188, s[8:9]
	v_cndmask_b32_e64 v56, v78, v189, s[10:11]
	v_cndmask_b32_e64 v56, v56, v190, s[4:5]
	v_cndmask_b32_e64 v56, v56, v192, s[6:7]
	v_cndmask_b32_e64 v188, v56, v193, s[8:9]
	v_cndmask_b32_e64 v56, v76, v194, s[10:11]
	v_cndmask_b32_e64 v56, v56, v195, s[4:5]
	v_cndmask_b32_e64 v56, v56, v196, s[6:7]
	v_cndmask_b32_e64 v190, v56, v197, s[8:9]
	v_cndmask_b32_e64 v56, v74, v198, s[10:11]
	v_cndmask_b32_e64 v56, v56, v200, s[4:5]
	v_cndmask_b32_e64 v56, v56, v201, s[6:7]
	v_cndmask_b32_e64 v192, v56, v204, s[8:9]
	v_cndmask_b32_e64 v56, v72, v205, s[10:11]
	v_cndmask_b32_e64 v56, v56, v206, s[4:5]
	v_cndmask_b32_e64 v56, v56, v207, s[6:7]
	v_cndmask_b32_e64 v194, v56, v163, s[8:9]
	v_cndmask_b32_e64 v56, v56, 0, s[8:9]
	v_mul_f32_e32 v196, 0x437f0000, v199
	v_mov_b32_e32 v159, v154
	v_cndmask_b32_e64 v7, v56, v7, s[6:7]
	v_pk_fma_f32 v[56:57], v[158:159], v[196:197], 0.5 op_sel_hi:[1,0,0]
	v_mov_b32_e32 v157, v155
	v_pk_fma_f32 v[154:155], v[150:151], v[196:197], 0.5 op_sel_hi:[1,0,0]
	v_pk_fma_f32 v[150:151], v[150:151], v[194:195], v[152:153] op_sel_hi:[1,0,1]
	v_mul_f32_e32 v152, 0x437f0000, v191
	v_mov_b32_e32 v149, v144
	v_cvt_u32_f32_sdwa v163, v57 dst_sel:WORD_1 dst_unused:UNUSED_PAD src0_sel:DWORD
	v_cvt_u32_f32_e32 v179, v56
	v_pk_fma_f32 v[56:57], v[158:159], v[194:195], v[156:157] op_sel_hi:[1,0,1]
	v_cvt_u32_f32_sdwa v156, v155 dst_sel:WORD_1 dst_unused:UNUSED_PAD src0_sel:DWORD
	v_cvt_u32_f32_e32 v157, v154
	v_pk_fma_f32 v[154:155], v[148:149], v[152:153], 0.5 op_sel_hi:[1,0,0]
	v_mov_b32_e32 v147, v145
	v_cvt_u32_f32_e32 v153, v154
	v_pk_fma_f32 v[144:145], v[148:149], v[192:193], v[146:147] op_sel_hi:[1,0,1]
	v_mov_b32_e32 v139, v134
	v_mov_b32_e32 v137, v135
	v_pk_fma_f32 v[146:147], v[140:141], v[152:153], 0.5 op_sel_hi:[1,0,0]
	v_pk_fma_f32 v[140:141], v[140:141], v[192:193], v[142:143] op_sel_hi:[1,0,1]
	v_mul_f32_e32 v142, 0x437f0000, v182
	v_cvt_u32_f32_sdwa v148, v147 dst_sel:WORD_1 dst_unused:UNUSED_PAD src0_sel:DWORD
	v_cvt_u32_f32_e32 v149, v146
	v_pk_fma_f32 v[146:147], v[138:139], v[142:143], 0.5 op_sel_hi:[1,0,0]
	v_pk_fma_f32 v[134:135], v[138:139], v[190:191], v[136:137] op_sel_hi:[1,0,1]
	v_cvt_u32_f32_e32 v143, v146
	v_mov_b32_e32 v129, v124
	v_mov_b32_e32 v127, v125
	v_pk_fma_f32 v[124:125], v[128:129], v[188:189], v[126:127] op_sel_hi:[1,0,1]
	v_pk_fma_f32 v[136:137], v[130:131], v[142:143], 0.5 op_sel_hi:[1,0,0]
	v_pk_fma_f32 v[130:131], v[130:131], v[190:191], v[132:133] op_sel_hi:[1,0,1]
	v_mul_f32_e32 v132, 0x437f0000, v117
	v_cvt_u32_f32_sdwa v138, v137 dst_sel:WORD_1 dst_unused:UNUSED_PAD src0_sel:DWORD
	v_cvt_u32_f32_e32 v139, v136
	v_pk_fma_f32 v[136:137], v[128:129], v[132:133], 0.5 op_sel_hi:[1,0,0]
	v_mov_b32_e32 v119, v114
	v_cvt_u32_f32_e32 v133, v136
	v_mov_b32_e32 v117, v115
	v_cndmask_b32_e64 v7, v7, v15, s[4:5]
	v_pk_fma_f32 v[114:115], v[118:119], v[186:187], v[116:117] op_sel_hi:[1,0,1]
	v_pk_fma_f32 v[126:127], v[120:121], v[132:133], 0.5 op_sel_hi:[1,0,0]
	v_pk_fma_f32 v[120:121], v[120:121], v[188:189], v[122:123] op_sel_hi:[1,0,1]
	v_mul_f32_e32 v122, 0x437f0000, v109
	v_cvt_u32_f32_sdwa v128, v127 dst_sel:WORD_1 dst_unused:UNUSED_PAD src0_sel:DWORD
	v_cvt_u32_f32_e32 v129, v126
	v_pk_fma_f32 v[126:127], v[118:119], v[122:123], 0.5 op_sel_hi:[1,0,0]
	v_mov_b32_e32 v109, v104
	v_cvt_u32_f32_sdwa v123, v127 dst_sel:WORD_1 dst_unused:UNUSED_PAD src0_sel:DWORD
	v_cndmask_b32_e64 v72, v7, v23, s[10:11]
	v_cndmask_b32_e64 v7, v192, v39, s[8:9]
	v_cndmask_b32_e64 v7, v7, v47, s[6:7]
	v_pk_fma_f32 v[116:117], v[110:111], v[122:123], 0.5 op_sel_hi:[1,0,0]
	v_pk_fma_f32 v[110:111], v[110:111], v[186:187], v[112:113] op_sel_hi:[1,0,1]
	v_mul_f32_e32 v112, 0x437f0000, v107
	v_cvt_u32_f32_sdwa v118, v117 dst_sel:WORD_1 dst_unused:UNUSED_PAD src0_sel:DWORD
	v_cvt_u32_f32_e32 v119, v116
	v_pk_fma_f32 v[116:117], v[108:109], v[112:113], 0.5 op_sel_hi:[1,0,0]
	v_cndmask_b32_e64 v7, v7, v61, s[4:5]
	v_cvt_u32_f32_e32 v113, v116
	v_cndmask_b32_e64 v74, v7, v97, s[10:11]
	v_cndmask_b32_e64 v7, v190, v171, s[8:9]
	v_cndmask_b32_e64 v7, v7, v177, s[6:7]
	v_mov_b32_e32 v107, v105
	v_cndmask_b32_e64 v7, v7, v215, s[4:5]
	v_pk_fma_f32 v[104:105], v[108:109], v[184:185], v[106:107] op_sel_hi:[1,0,1]
	v_pk_fma_f32 v[106:107], v[100:101], v[112:113], 0.5 op_sel_hi:[1,0,0]
	v_pk_fma_f32 v[100:101], v[100:101], v[184:185], v[102:103] op_sel_hi:[1,0,1]
	v_mul_f32_e32 v102, 0x437f0000, v99
	v_mov_b32_e32 v99, v66
	v_cndmask_b32_e64 v76, v7, v216, s[10:11]
	v_cndmask_b32_e64 v7, v188, v217, s[8:9]
	v_cvt_u32_f32_sdwa v108, v107 dst_sel:WORD_1 dst_unused:UNUSED_PAD src0_sel:DWORD
	v_cvt_u32_f32_e32 v109, v106
	v_pk_fma_f32 v[106:107], v[98:99], v[102:103], 0.5 op_sel_hi:[1,0,0]
	v_cndmask_b32_e64 v7, v7, v218, s[6:7]
	v_cvt_u32_f32_e32 v103, v106
	v_cndmask_b32_e64 v7, v7, v219, s[4:5]
	v_cndmask_b32_e64 v78, v7, v220, s[10:11]
	v_cndmask_b32_e64 v7, v186, v221, s[8:9]
	v_cndmask_b32_e64 v7, v7, v222, s[6:7]
; DI unsigned cvtpk(float lo, float hi) { unsigned r; asm volatile("v_cvt_pk_bf16_f32 %0, %1, %2" : "=v"(r) : "v"(lo), "v"(hi)); return r; }
; DI void lru_tile(const Params& p, unsigned char* shm, int c, int nb, const LruPar par) {
;     ...
;         for (int rt = 0; rt < 8; ++rt) {
;             const f32x2 cr2 = {carry[rt], carry[rt]}, pf2 = {pref[rt] * 255.f, pref[rt] * 255.f}, half2 = {0.5f, 0.5f};
; #pragma unroll
;             for (int jp = 0; jp < 2; ++jp) {
;                 const f32x2 pc2 = {pc[rt][2 * jp], pc[rt][2 * jp + 1]}, hl2 = {hl[rt][2 * jp], hl[rt][2 * jp + 1]};
;                 const f32x2 hf = pc2 * cr2 + hl2, pq = pc2 * pf2 + half2;
;                 const unsigned q0 = (unsigned)pq[0], q1 = (unsigned)pq[1];
;                 if (d == 0) { hsum[rt][2 * jp] = hf[0]; hsum[rt][2 * jp + 1] = hf[1]; ppk[rt][jp] = q0 | (q1 << 16); }
;                 else {
;                     const int lo = (rt * 16 + 4 * q + 2 * jp) * LDU + chl;
;                     const unsigned w = cvtpk(hsum[rt][2 * jp] + hf[0], hsum[rt][2 * jp + 1] + hf[1]);
;                     OS[lo] = (unsigned short)(w & 0xffffu); OS[lo + LDU] = (unsigned short)(w >> 16);
;                     const unsigned pw = ppk[rt][jp] | (q0 << 8) | (q1 << 24);
;                     PS[lo] = (unsigned short)(pw & 0xffffu); PS[lo + LDU] = (unsigned short)(pw >> 16);
;                 }
	v_mov_b32_e32 v97, v67
	v_cndmask_b32_e64 v7, v7, v223, s[4:5]
	v_pk_fma_f32 v[66:67], v[98:99], v[238:239], v[96:97] op_sel_hi:[1,0,1]
	v_pk_fma_f32 v[96:97], v[62:63], v[102:103], 0.5 op_sel_hi:[1,0,0]
	v_pk_fma_f32 v[62:63], v[62:63], v[238:239], v[64:65] op_sel_hi:[1,0,1]
	v_mul_f32_e32 v64, 0x437f0000, v181
	v_mov_b32_e32 v61, v54
	v_cndmask_b32_e64 v80, v7, v224, s[10:11]
	v_cndmask_b32_e64 v7, v184, v225, s[8:9]
	v_cvt_u32_f32_sdwa v98, v97 dst_sel:WORD_1 dst_unused:UNUSED_PAD src0_sel:DWORD
	v_cvt_u32_f32_e32 v99, v96
	v_pk_fma_f32 v[96:97], v[60:61], v[64:65], 0.5 op_sel_hi:[1,0,0]
	v_cndmask_b32_e64 v7, v7, v226, s[6:7]
	v_cvt_u32_f32_sdwa v65, v97 dst_sel:WORD_1 dst_unused:UNUSED_PAD src0_sel:DWORD
	v_cndmask_b32_e64 v7, v7, v227, s[4:5]
	v_cndmask_b32_e64 v84, v7, v228, s[10:11]
	v_cndmask_b32_e64 v7, v238, v229, s[8:9]
	v_cndmask_b32_e64 v7, v7, v230, s[6:7]
	v_mov_b32_e32 v59, v55
	v_cndmask_b32_e64 v7, v7, v231, s[4:5]
	v_pk_fma_f32 v[54:55], v[60:61], v[178:179], v[58:59] op_sel_hi:[1,0,1]
	v_pk_fma_f32 v[58:59], v[50:51], v[64:65], 0.5 op_sel_hi:[1,0,0]
	v_pk_fma_f32 v[50:51], v[50:51], v[178:179], v[52:53] op_sel_hi:[1,0,1]
	v_mul_f32_e32 v52, 0x437f0000, v31
	v_mov_b32_e32 v171, v49
	v_cndmask_b32_e64 v88, v7, v232, s[10:11]
	v_cndmask_b32_e64 v7, v178, v233, s[8:9]
	v_cvt_u32_f32_sdwa v60, v59 dst_sel:WORD_1 dst_unused:UNUSED_PAD src0_sel:DWORD
	v_cvt_u32_f32_e32 v61, v58
	v_pk_fma_f32 v[58:59], v[170:171], v[52:53], 0.5 op_sel_hi:[1,0,0]
	v_cndmask_b32_e64 v7, v7, v234, s[6:7]
	v_cvt_u32_f32_e32 v49, v58
	v_cndmask_b32_e64 v7, v7, v235, s[4:5]
	v_cndmask_b32_e64 v90, v7, v236, s[10:11]
	v_cvt_u32_f32_e32 v31, v59
	v_pk_fma_f32 v[58:59], v[170:171], v[90:91], v[168:169] op_sel_hi:[1,0,1]
	v_add_lshl_u32 v53, v48, v95, 1
	v_pk_add_f32 v[50:51], v[50:51], v[58:59]
	v_lshlrev_b32_e32 v48, 8, v49
	v_cvt_pk_bf16_f32 v50, v50, v51
	v_add_u32_e32 v58, s68, v53
	v_or3_b32 v48, v60, v61, v48
	ds_write_b16 v58, v50
	ds_write_b16_d16_hi v58, v50 offset:272
	v_lshl_or_b32 v31, v31, 24, v48
	ds_write_b16 v68, v48 offset:34816
	ds_write_b16_d16_hi v68, v31 offset:35088
	v_pk_fma_f32 v[48:49], v[160:161], v[52:53], 0.5 op_sel_hi:[1,0,0]
	v_cvt_u32_f32_e32 v96, v96
	v_cvt_u32_f32_e32 v50, v48
	v_cvt_u32_f32_e32 v31, v49
	v_pk_fma_f32 v[48:49], v[160:161], v[90:91], v[166:167] op_sel_hi:[1,0,1]
	v_cvt_u32_f32_sdwa v7, v155 dst_sel:WORD_1 dst_unused:UNUSED_PAD src0_sel:DWORD
	v_pk_add_f32 v[48:49], v[54:55], v[48:49]
	v_cvt_u32_f32_sdwa v15, v147 dst_sel:WORD_1 dst_unused:UNUSED_PAD src0_sel:DWORD
	v_cvt_pk_bf16_f32 v48, v48, v49
	ds_write_b16 v58, v48 offset:544
	ds_write_b16_d16_hi v58, v48 offset:816
	v_lshlrev_b32_e32 v48, 8, v50
	v_or3_b32 v48, v65, v96, v48
	v_cvt_u32_f32_sdwa v23, v137 dst_sel:WORD_1 dst_unused:UNUSED_PAD src0_sel:DWORD
	v_cvt_u32_f32_e32 v126, v126
	v_cvt_u32_f32_sdwa v39, v117 dst_sel:WORD_1 dst_unused:UNUSED_PAD src0_sel:DWORD
	v_cvt_u32_f32_sdwa v47, v107 dst_sel:WORD_1 dst_unused:UNUSED_PAD src0_sel:DWORD
	v_lshl_or_b32 v31, v31, 24, v48
	ds_write_b16 v68, v48 offset:35360
	ds_write_b16_d16_hi v68, v31 offset:35632
	v_mul_f32_e32 v48, 0x437f0000, v162
	v_mov_b32_e32 v177, v208
	v_pk_fma_f32 v[50:51], v[176:177], v[48:49], 0.5 op_sel_hi:[1,0,0]
	s_nop 0
	v_cvt_u32_f32_e32 v49, v50
	v_cvt_u32_f32_e32 v31, v51
	v_pk_fma_f32 v[50:51], v[176:177], v[88:89], v[174:175] op_sel_hi:[1,0,1]
	v_lshlrev_b32_e32 v49, 8, v49
	v_pk_add_f32 v[50:51], v[62:63], v[50:51]
	v_or3_b32 v49, v98, v99, v49
	v_cvt_pk_bf16_f32 v50, v50, v51
	ds_write_b16 v58, v50 offset:4352
	ds_write_b16_d16_hi v58, v50 offset:4624
	v_lshl_or_b32 v31, v31, 24, v49
	ds_write_b16 v68, v49 offset:39168
	ds_write_b16_d16_hi v68, v31 offset:39440
	v_pk_fma_f32 v[48:49], v[164:165], v[48:49], 0.5 op_sel_hi:[1,0,0]
	s_nop 0
	v_cvt_u32_f32_e32 v50, v48
	v_cvt_u32_f32_e32 v31, v49
	v_pk_fma_f32 v[48:49], v[164:165], v[88:89], v[172:173] op_sel_hi:[1,0,1]
	s_nop 0
	v_pk_add_f32 v[48:49], v[66:67], v[48:49]
	s_nop 0
	v_cvt_pk_bf16_f32 v48, v48, v49
	ds_write_b16 v58, v48 offset:4896
	ds_write_b16_d16_hi v58, v48 offset:5168
	v_lshlrev_b32_e32 v48, 8, v50
	v_or3_b32 v47, v47, v103, v48
	v_lshl_or_b32 v31, v31, 24, v47
	ds_write_b16 v68, v47 offset:39712
	ds_write_b16_d16_hi v68, v31 offset:39984
	v_mul_f32_e32 v48, 0x437f0000, v91
	v_mov_b32_e32 v47, v209
	v_pk_fma_f32 v[50:51], v[46:47], v[48:49], 0.5 op_sel_hi:[1,0,0]
	v_pk_fma_f32 v[44:45], v[46:47], v[84:85], v[44:45] op_sel_hi:[1,0,1]
	v_cvt_u32_f32_e32 v49, v50
	v_cvt_u32_f32_e32 v31, v51
	v_pk_add_f32 v[44:45], v[100:101], v[44:45]
	v_pk_fma_f32 v[40:41], v[42:43], v[84:85], v[40:41] op_sel_hi:[1,0,1]
	v_cvt_pk_bf16_f32 v44, v44, v45
	ds_write_b16 v58, v44 offset:8704
	ds_write_b16_d16_hi v58, v44 offset:8976
	v_lshlrev_b32_e32 v44, 8, v49
	v_or3_b32 v44, v108, v109, v44
	v_lshl_or_b32 v31, v31, 24, v44
	ds_write_b16 v68, v44 offset:43520
	ds_write_b16_d16_hi v68, v31 offset:43792
	v_pk_fma_f32 v[44:45], v[42:43], v[48:49], 0.5 op_sel_hi:[1,0,0]
	v_pk_add_f32 v[40:41], v[104:105], v[40:41]
	v_cvt_u32_f32_e32 v44, v44
	v_cvt_u32_f32_e32 v31, v45
	v_cvt_pk_bf16_f32 v40, v40, v41
	ds_write_b16 v58, v40 offset:9248
	ds_write_b16_d16_hi v58, v40 offset:9520
	v_lshlrev_b32_e32 v40, 8, v44
	v_or3_b32 v39, v39, v113, v40
	v_lshl_or_b32 v31, v31, 24, v39
	ds_write_b16 v68, v39 offset:44064
	ds_write_b16_d16_hi v68, v31 offset:44336
	v_mul_f32_e32 v40, 0x437f0000, v89
	v_mov_b32_e32 v39, v210
	v_pk_fma_f32 v[42:43], v[38:39], v[40:41], 0.5 op_sel_hi:[1,0,0]
	v_pk_fma_f32 v[36:37], v[38:39], v[80:81], v[36:37] op_sel_hi:[1,0,1]
	v_cvt_u32_f32_e32 v41, v42
	v_cvt_u32_f32_e32 v31, v43
	v_pk_add_f32 v[36:37], v[110:111], v[36:37]
; DI void lru_tile(const Params& p, unsigned char* shm, int c, int nb, const LruPar par) {
;     ...
;         const int cgp = tid & 15, rg = tid >> 4, ch = nb * 128 + cgp * 8;
;         const float* cw = p.in[3]; const float* cb = p.in[4];
;         float w[4][8], bias[8];
; #pragma unroll
;         for (int tp = 0; tp < 4; ++tp) { const f32x4 a = *(const f32x4*)(cw + tp * 2048 + ch), b = *(const f32x4*)(cw + tp * 2048 + ch + 4);
;             w[tp][0] = a[0]; w[tp][1] = a[1]; w[tp][2] = a[2]; w[tp][3] = a[3]; w[tp][4] = b[0]; w[tp][5] = b[1]; w[tp][6] = b[2]; w[tp][7] = b[3]; }
;         { const f32x4 a = *(const f32x4*)(cb + ch), b = *(const f32x4*)(cb + ch + 4);
;             bias[0] = a[0]; bias[1] = a[1]; bias[2] = a[2]; bias[3] = a[3]; bias[4] = b[0]; bias[5] = b[1]; bias[6] = b[2]; bias[7] = b[3]; }
;         float xr[7][8];
; #pragma unroll
;         for (int k = 0; k < 7; ++k) { const int t = c * 128 + rg * 4 - 2 + k;
;             u32x4 v = {0u, 0u, 0u, 0u};
;             if (t >= 0 && t < S) v = *(const u32x4*)(ZU + (size_t)(nb >> 1) * S * 256 + (size_t)t * 256 + (nb & 1) * 128 + cgp * 8);
; #pragma unroll
;             for (int i = 0; i < 4; ++i) { xr[k][2 * i] = bflo(v[i]); xr[k][2 * i + 1] = bfhi(v[i]); } }
;     ...
;         for (int rt = 0; rt < 8; ++rt) {
;             const f32x2 cr2 = {carry[rt], carry[rt]}, pf2 = {pref[rt] * 255.f, pref[rt] * 255.f}, half2 = {0.5f, 0.5f};
; #pragma unroll
;             for (int jp = 0; jp < 2; ++jp) {
;                 const f32x2 pc2 = {pc[rt][2 * jp], pc[rt][2 * jp + 1]}, hl2 = {hl[rt][2 * jp], hl[rt][2 * jp + 1]};
;                 const f32x2 hf = pc2 * cr2 + hl2, pq = pc2 * pf2 + half2;
;                 const unsigned q0 = (unsigned)pq[0], q1 = (unsigned)pq[1];
;                 if (d == 0) { hsum[rt][2 * jp] = hf[0]; hsum[rt][2 * jp + 1] = hf[1]; ppk[rt][jp] = q0 | (q1 << 16); }
;                 else {
;                     const int lo = (rt * 16 + 4 * q + 2 * jp) * LDU + chl;
;                     const unsigned w = cvtpk(hsum[rt][2 * jp] + hf[0], hsum[rt][2 * jp + 1] + hf[1]);
;                     OS[lo] = (unsigned short)(w & 0xffffu); OS[lo + LDU] = (unsigned short)(w >> 16);
;                     const unsigned pw = ppk[rt][jp] | (q0 << 8) | (q1 << 24);
;                     PS[lo] = (unsigned short)(pw & 0xffffu); PS[lo + LDU] = (unsigned short)(pw >> 16);
;                 }
	v_pk_fma_f32 v[32:33], v[34:35], v[80:81], v[32:33] op_sel_hi:[1,0,1]
	v_cvt_pk_bf16_f32 v36, v36, v37
	ds_write_b16 v58, v36 offset:13056
	ds_write_b16_d16_hi v58, v36 offset:13328
	v_lshlrev_b32_e32 v36, 8, v41
	v_or3_b32 v36, v118, v119, v36
	v_lshl_or_b32 v31, v31, 24, v36
	ds_write_b16 v68, v36 offset:47872
	ds_write_b16_d16_hi v68, v31 offset:48144
	v_pk_fma_f32 v[36:37], v[34:35], v[40:41], 0.5 op_sel_hi:[1,0,0]
	v_pk_add_f32 v[32:33], v[114:115], v[32:33]
	v_cvt_u32_f32_e32 v36, v36
	v_cvt_u32_f32_e32 v31, v37
	v_cvt_pk_bf16_f32 v32, v32, v33
	ds_write_b16 v58, v32 offset:13600
	ds_write_b16_d16_hi v58, v32 offset:13872
	v_lshlrev_b32_e32 v32, 8, v36
	v_or3_b32 v32, v123, v126, v32
	v_lshl_or_b32 v31, v31, 24, v32
	ds_write_b16 v68, v32 offset:48416
	ds_write_b16_d16_hi v68, v31 offset:48688
	v_mul_f32_e32 v32, 0x437f0000, v85
	v_mov_b32_e32 v31, v211
	v_pk_fma_f32 v[34:35], v[30:31], v[32:33], 0.5 op_sel_hi:[1,0,0]
	v_pk_fma_f32 v[28:29], v[30:31], v[78:79], v[28:29] op_sel_hi:[1,0,1]
	v_cvt_u32_f32_e32 v34, v34
	v_cvt_u32_f32_e32 v33, v35
	v_pk_add_f32 v[28:29], v[120:121], v[28:29]
	v_pk_fma_f32 v[24:25], v[26:27], v[78:79], v[24:25] op_sel_hi:[1,0,1]
	v_cvt_pk_bf16_f32 v28, v28, v29
	ds_write_b16 v58, v28 offset:17408
	ds_write_b16_d16_hi v58, v28 offset:17680
	v_lshlrev_b32_e32 v28, 8, v34
	v_or3_b32 v28, v128, v129, v28
	v_lshl_or_b32 v29, v33, 24, v28
	ds_write_b16 v68, v28 offset:52224
	ds_write_b16_d16_hi v68, v29 offset:52496
	v_pk_fma_f32 v[28:29], v[26:27], v[32:33], 0.5 op_sel_hi:[1,0,0]
	v_pk_add_f32 v[24:25], v[124:125], v[24:25]
	v_cvt_u32_f32_e32 v28, v28
	v_cvt_u32_f32_e32 v29, v29
	v_cvt_pk_bf16_f32 v24, v24, v25
	ds_write_b16 v58, v24 offset:17952
	ds_write_b16_d16_hi v58, v24 offset:18224
	v_lshlrev_b32_e32 v24, 8, v28
	v_or3_b32 v23, v23, v133, v24
	v_lshl_or_b32 v24, v29, 24, v23
	ds_write_b16 v68, v23 offset:52768
	ds_write_b16_d16_hi v68, v24 offset:53040
	v_mul_f32_e32 v24, 0x437f0000, v81
	v_mov_b32_e32 v23, v212
	v_pk_fma_f32 v[26:27], v[22:23], v[24:25], 0.5 op_sel_hi:[1,0,0]
	v_pk_fma_f32 v[20:21], v[22:23], v[76:77], v[20:21] op_sel_hi:[1,0,1]
	v_cvt_u32_f32_e32 v26, v26
	v_cvt_u32_f32_e32 v25, v27
	v_pk_add_f32 v[20:21], v[130:131], v[20:21]
	v_pk_fma_f32 v[16:17], v[18:19], v[76:77], v[16:17] op_sel_hi:[1,0,1]
	v_cvt_pk_bf16_f32 v20, v20, v21
	ds_write_b16 v58, v20 offset:21760
	ds_write_b16_d16_hi v58, v20 offset:22032
	v_lshlrev_b32_e32 v20, 8, v26
	v_or3_b32 v20, v138, v139, v20
	v_lshl_or_b32 v21, v25, 24, v20
	ds_write_b16 v68, v20 offset:56576
	ds_write_b16_d16_hi v68, v21 offset:56848
	v_pk_fma_f32 v[20:21], v[18:19], v[24:25], 0.5 op_sel_hi:[1,0,0]
	v_pk_add_f32 v[16:17], v[134:135], v[16:17]
	v_cvt_u32_f32_e32 v20, v20
	v_cvt_u32_f32_e32 v21, v21
	v_cvt_pk_bf16_f32 v16, v16, v17
	ds_write_b16 v58, v16 offset:22304
	ds_write_b16_d16_hi v58, v16 offset:22576
	v_lshlrev_b32_e32 v16, 8, v20
	v_or3_b32 v15, v15, v143, v16
	v_lshl_or_b32 v16, v21, 24, v15
	ds_write_b16 v68, v15 offset:57120
	ds_write_b16_d16_hi v68, v16 offset:57392
	v_mul_f32_e32 v16, 0x437f0000, v79
	v_mov_b32_e32 v15, v213
	v_pk_fma_f32 v[18:19], v[14:15], v[16:17], 0.5 op_sel_hi:[1,0,0]
	v_pk_fma_f32 v[12:13], v[14:15], v[74:75], v[12:13] op_sel_hi:[1,0,1]
	v_cvt_u32_f32_e32 v18, v18
	v_cvt_u32_f32_e32 v17, v19
	v_pk_add_f32 v[12:13], v[140:141], v[12:13]
	v_pk_fma_f32 v[8:9], v[10:11], v[74:75], v[8:9] op_sel_hi:[1,0,1]
	v_cvt_pk_bf16_f32 v12, v12, v13
	ds_write_b16 v58, v12 offset:26112
	ds_write_b16_d16_hi v58, v12 offset:26384
	v_lshlrev_b32_e32 v12, 8, v18
	v_or3_b32 v12, v148, v149, v12
	v_lshl_or_b32 v13, v17, 24, v12
	ds_write_b16 v68, v12 offset:60928
	ds_write_b16_d16_hi v68, v13 offset:61200
	v_pk_fma_f32 v[12:13], v[10:11], v[16:17], 0.5 op_sel_hi:[1,0,0]
	v_pk_add_f32 v[8:9], v[144:145], v[8:9]
	v_cvt_u32_f32_e32 v12, v12
	v_cvt_u32_f32_e32 v13, v13
	v_cvt_pk_bf16_f32 v8, v8, v9
	ds_write_b16 v58, v8 offset:26656
	ds_write_b16_d16_hi v58, v8 offset:26928
	v_lshlrev_b32_e32 v8, 8, v12
	v_or3_b32 v7, v7, v153, v8
	v_lshl_or_b32 v8, v13, 24, v7
	ds_write_b16 v68, v7 offset:61472
	ds_write_b16_d16_hi v68, v8 offset:61744
	v_mul_f32_e32 v8, 0x437f0000, v77
	v_mov_b32_e32 v7, v214
	v_pk_fma_f32 v[10:11], v[6:7], v[8:9], 0.5 op_sel_hi:[1,0,0]
	v_pk_fma_f32 v[4:5], v[6:7], v[72:73], v[4:5] op_sel_hi:[1,0,1]
	v_cvt_u32_f32_e32 v10, v10
	v_cvt_u32_f32_e32 v9, v11
	v_pk_add_f32 v[4:5], v[150:151], v[4:5]
	v_pk_fma_f32 v[0:1], v[2:3], v[72:73], v[0:1] op_sel_hi:[1,0,1]
	v_cvt_pk_bf16_f32 v4, v4, v5
	ds_write_b16 v58, v4 offset:30464
	ds_write_b16_d16_hi v58, v4 offset:30736
	v_lshlrev_b32_e32 v4, 8, v10
	v_or3_b32 v4, v156, v157, v4
	v_lshl_or_b32 v5, v9, 24, v4
	ds_write_b16 v68, v4 offset:65280
	v_add_u32_e32 v4, 0x10010, v68
	ds_write_b16_d16_hi v4, v5
	v_pk_fma_f32 v[4:5], v[2:3], v[8:9], 0.5 op_sel_hi:[1,0,0]
	v_pk_add_f32 v[0:1], v[56:57], v[0:1]
	v_cvt_u32_f32_e32 v4, v4
	v_cvt_u32_f32_e32 v5, v5
	v_cvt_pk_bf16_f32 v0, v0, v1
	ds_write_b16 v58, v0 offset:31008
	ds_write_b16_d16_hi v58, v0 offset:31280
	v_lshlrev_b32_e32 v0, 8, v4
	v_add_u32_e32 v2, 0, v53
	v_or3_b32 v0, v163, v179, v0
	v_add_u32_e32 v2, 0x7920, v2
	v_lshl_or_b32 v1, v5, 24, v0
	ds_write_b16 v2, v0 offset:34816
	ds_write_b16_d16_hi v2, v1 offset:35088
	s_cmp_eq_u32 s24, 0x100
	s_cbranch_scc0 .Llru_nopre
	s_add_i32 s78, s69, s24
	s_cmpk_lt_i32 s78, 0x800
	s_cbranch_scc0 .Llru_nopre
	v_lshlrev_b32_e32 v250, 3, v202
	v_and_b32_e32 v250, 0x78, v250
	v_or_b32_e32 v250, s38, v250
	v_lshlrev_b32_e32 v250, 2, v250
	s_add_u32 s84, s20, 0x2000
	s_addc_u32 s85, s21, 0
	s_add_u32 s86, s20, 0x4000
	s_addc_u32 s87, s21, 0
	s_add_u32 s88, s20, 0x6000
	s_addc_u32 s89, s21, 0
	s_ashr_i32 s79, s78, 4
	v_and_b32_e32 v251, -4, v94
	v_lshl_add_u32 v251, s79, 7, v251
	v_add_u32_e32 v251, 4, v251
	global_load_dwordx4 v[40:43], v[248:249], off offset:-1024 nt
	global_load_dwordx4 v[44:47], v[248:249], off offset:-512 nt
	global_load_dwordx4 v[48:51], v[248:249], off nt
	global_load_dwordx4 v[52:55], v[248:249], off offset:512 nt
	global_load_dwordx4 v[56:59], v[248:249], off offset:1024 nt
	global_load_dwordx4 v[60:63], v[248:249], off offset:1536 nt
	v_mov_b32_e32 v64, 0
	v_mov_b32_e32 v65, 0
	v_mov_b32_e32 v66, 0
	v_mov_b32_e32 v67, 0
	v_cmp_gt_u32_e32 vcc, s65, v251
	s_and_saveexec_b64 s[80:81], vcc
	global_load_dwordx4 v[64:67], v[248:249], off offset:2048 nt
	s_or_b64 exec, exec, s[80:81]
	global_load_dwordx4 v[12:15], v250, s[84:85]
	global_load_dwordx4 v[0:3], v250, s[84:85] offset:16
	global_load_dwordx4 v[32:35], v250, s[86:87]
	global_load_dwordx4 v[24:27], v250, s[86:87] offset:16
	global_load_dwordx4 v[16:19], v250, s[88:89]
	global_load_dwordx4 v[4:7], v250, s[88:89] offset:16
	global_load_dwordx4 v[28:31], v250, s[20:21] offset:16
	global_load_dwordx4 v[8:11], v250, s[22:23] offset:16
	global_load_dwordx4 v[36:39], v250, s[20:21]
	global_load_dwordx4 v[20:23], v250, s[22:23]
	s_mov_b32 s71, 1
